# D phases: split-K partial slabs stored write-through (sc1) and read with sc1 loads, so the mid-phase barrier needs no L2 writeback
# baseline (speedup 1.0000x reference)
;     __device__ __forceinline__ void store_partial(const f32x4 (&acc)[2][2][4][2], int tid, int wid, int lane) const {
;         typedef unsigned u32x4v __attribute__((ext_vector_type(4)));
;         asm volatile("" : "+v"(tid));
;         const __amdgpu_buffer_rsrc_t r = __builtin_amdgcn_make_buffer_rsrc((void*)(slab + (size_t)c * 65536), 0, 262144, 0x00020000);
;         const int vo = tid * 16;
; #pragma unroll
;         for (int ai = 0; ai < 2; ++ai)
; #pragma unroll
;             for (int bj = 0; bj < 2; ++bj)
; #pragma unroll
;                 for (int m = 0; m < 4; ++m) {
;                     const f32x4 p0 = acc[ai][bj][m][0], p1 = acc[ai][bj][m][1]; u32x4v w;
;                     asm("v_cvt_pk_bf16_f32 %0, %1, %2" : "=v"(w.x) : "v"(p0[0]), "v"(p0[1])); asm("v_cvt_pk_bf16_f32 %0, %1, %2" : "=v"(w.y) : "v"(p0[2]), "v"(p0[3]));
;                     asm("v_cvt_pk_bf16_f32 %0, %1, %2" : "=v"(w.z) : "v"(p1[0]), "v"(p1[1])); asm("v_cvt_pk_bf16_f32 %0, %1, %2" : "=v"(w.w) : "v"(p1[2]), "v"(p1[3]));
;                     __builtin_amdgcn_raw_buffer_store_b128(w, r, vo, ((ai * 2 + bj) * 4 + m) * 8192, 0);
;                 }
;     }
.LBB0_394:
	s_and_b64 vcc, exec, s[8:9]
	s_cbranch_vccz .LBB0_390
	v_mov_b32_e32 v128, v171
	v_readlane_b32 s60, v254, 31
	v_lshlrev_b32_e32 v128, 4, v128
	v_cvt_pk_bf16_f32 v96, v96, v97
	v_cvt_pk_bf16_f32 v97, v98, v99
	v_cvt_pk_bf16_f32 v98, v100, v101
	v_cvt_pk_bf16_f32 v99, v102, v103
	v_readlane_b32 s61, v254, 32
	v_readlane_b32 s62, v254, 33
	v_readlane_b32 s63, v254, 34
	s_movk_i32 s2, 0x2000
	v_cvt_pk_bf16_f32 v32, v32, v33
	v_cvt_pk_bf16_f32 v33, v34, v35
	v_cvt_pk_bf16_f32 v34, v36, v37
	v_cvt_pk_bf16_f32 v35, v38, v39
	s_nop 3
	buffer_store_dwordx4 v[96:99], v128, s[60:63], 0 offen sc1
	v_cvt_pk_bf16_f32 v28, v28, v29
	v_cvt_pk_bf16_f32 v29, v30, v31
	v_cvt_pk_bf16_f32 v30, v24, v25
	v_cvt_pk_bf16_f32 v31, v26, v27
	v_cvt_pk_bf16_f32 v20, v20, v21
	s_nop 1
	v_cvt_pk_bf16_f32 v96, v104, v105
	v_cvt_pk_bf16_f32 v97, v106, v107
	v_cvt_pk_bf16_f32 v98, v108, v109
	v_cvt_pk_bf16_f32 v99, v110, v111
	buffer_store_dwordx4 v[96:99], v128, s[60:63], s2 offen sc1
	s_movk_i32 s2, 0x4000
	v_cvt_pk_bf16_f32 v96, v112, v113
	v_cvt_pk_bf16_f32 v97, v114, v115
	v_cvt_pk_bf16_f32 v98, v116, v117
	v_cvt_pk_bf16_f32 v99, v118, v119
	buffer_store_dwordx4 v[96:99], v128, s[60:63], s2 offen sc1
	s_movk_i32 s2, 0x6000
	v_cvt_pk_bf16_f32 v96, v120, v121
	v_cvt_pk_bf16_f32 v97, v122, v123
	v_cvt_pk_bf16_f32 v98, v124, v125
	v_cvt_pk_bf16_f32 v99, v126, v127
	buffer_store_dwordx4 v[96:99], v128, s[60:63], s2 offen sc1
	s_mov_b32 s2, 0x8000
	buffer_store_dwordx4 v[32:35], v128, s[60:63], s2 offen sc1
	s_mov_b32 s2, 0xa000
	v_cvt_pk_bf16_f32 v32, v52, v53
	v_cvt_pk_bf16_f32 v33, v54, v55
	v_cvt_pk_bf16_f32 v34, v56, v57
	v_cvt_pk_bf16_f32 v35, v58, v59
	buffer_store_dwordx4 v[32:35], v128, s[60:63], s2 offen sc1
	s_mov_b32 s2, 0xc000
	v_cvt_pk_bf16_f32 v32, v72, v73
	v_cvt_pk_bf16_f32 v33, v74, v75
	v_cvt_pk_bf16_f32 v34, v80, v81
	v_cvt_pk_bf16_f32 v35, v82, v83
	buffer_store_dwordx4 v[32:35], v128, s[60:63], s2 offen sc1
	s_mov_b32 s2, 0xe000
	v_cvt_pk_bf16_f32 v32, v88, v89
	v_cvt_pk_bf16_f32 v33, v90, v91
	v_cvt_pk_bf16_f32 v34, v92, v93
	v_cvt_pk_bf16_f32 v35, v94, v95
	buffer_store_dwordx4 v[32:35], v128, s[60:63], s2 offen sc1
	s_mov_b32 s2, 0x10000
	v_cvt_pk_bf16_f32 v32, v84, v85
	v_cvt_pk_bf16_f32 v33, v86, v87
	v_cvt_pk_bf16_f32 v34, v76, v77
	v_cvt_pk_bf16_f32 v35, v78, v79
	buffer_store_dwordx4 v[32:35], v128, s[60:63], s2 offen sc1
	s_mov_b32 s2, 0x12000
	v_cvt_pk_bf16_f32 v32, v68, v69
	v_cvt_pk_bf16_f32 v33, v70, v71
	v_cvt_pk_bf16_f32 v34, v64, v65
	v_cvt_pk_bf16_f32 v35, v66, v67
	buffer_store_dwordx4 v[32:35], v128, s[60:63], s2 offen sc1
	s_mov_b32 s2, 0x14000
	v_cvt_pk_bf16_f32 v32, v60, v61
	v_cvt_pk_bf16_f32 v33, v62, v63
	v_cvt_pk_bf16_f32 v34, v48, v49
	v_cvt_pk_bf16_f32 v35, v50, v51
	buffer_store_dwordx4 v[32:35], v128, s[60:63], s2 offen sc1
	s_mov_b32 s2, 0x16000
	v_cvt_pk_bf16_f32 v32, v44, v45
	v_cvt_pk_bf16_f32 v33, v46, v47
	v_cvt_pk_bf16_f32 v34, v40, v41
	v_cvt_pk_bf16_f32 v35, v42, v43
	buffer_store_dwordx4 v[32:35], v128, s[60:63], s2 offen sc1
	s_mov_b32 s2, 0x18000
	buffer_store_dwordx4 v[28:31], v128, s[60:63], s2 offen sc1
	s_mov_b32 s2, 0x1a000
	v_cvt_pk_bf16_f32 v21, v22, v23
	v_cvt_pk_bf16_f32 v22, v16, v17
	v_cvt_pk_bf16_f32 v23, v18, v19
	buffer_store_dwordx4 v[20:23], v128, s[60:63], s2 offen sc1
	s_mov_b32 s2, 0x1c000
	v_cvt_pk_bf16_f32 v12, v12, v13
	v_cvt_pk_bf16_f32 v13, v14, v15
	v_cvt_pk_bf16_f32 v14, v8, v9
	v_cvt_pk_bf16_f32 v15, v10, v11
	buffer_store_dwordx4 v[12:15], v128, s[60:63], s2 offen sc1
	s_mov_b32 s2, 0x1e000
	v_cvt_pk_bf16_f32 v4, v4, v5
	v_cvt_pk_bf16_f32 v5, v6, v7
	v_cvt_pk_bf16_f32 v6, v0, v1
	v_cvt_pk_bf16_f32 v7, v2, v3
	buffer_store_dwordx4 v[4:7], v128, s[60:63], s2 offen sc1
	s_mov_b64 s[2:3], -1
	s_and_b64 vcc, exec, s[6:7]
	s_mov_b64 s[6:7], -1
	s_cbranch_vccz .LBB0_391

; __device__ __forceinline__ unsigned xb_ld(unsigned* p)              { return __hip_atomic_load(p, __ATOMIC_RELAXED, __HIP_MEMORY_SCOPE_AGENT); }
; __device__ __forceinline__ unsigned xb_add(unsigned* p, unsigned v) { return __hip_atomic_fetch_add(p, v, __ATOMIC_RELAXED, __HIP_MEMORY_SCOPE_AGENT); }
; #define XB_SPIN(cond, bar) do { unsigned _sp = 0; while (cond) { __builtin_amdgcn_s_sleep(1); \
;     if ((++_sp & 255u) == 0u) { if (xb_ld(&(bar)[XB_TMO])) break; if (_sp > XB_SPIN_CAP) { atomicAdd(&(bar)[XB_TMO], 1u); break; } } } } while (0)
; __device__ __forceinline__ void xcd_barrier(const XcdBarrier& b, const bool is_t0) {
;     asm volatile("s_waitcnt vmcnt(0)" ::: "memory");
;     __syncthreads();
;     if (is_t0) {
;         unsigned* bar = b.bar;
;         __builtin_amdgcn_s_waitcnt(0);
;         unsigned nloc = b.st[0], nx = b.st[1];
;         if (nloc == 0u) { xcd_barrier_complete(bar, b.x, nloc, nx); b.st[0] = nloc; b.st[1] = nx; }
;         const unsigned old = xb_add(&bar[XB_XSUB(b.x)], 1u);
;         const unsigned gen = old / nloc;
;         if (old + 1u == (gen + 1u) * nloc) {
;             __builtin_amdgcn_fence(__ATOMIC_RELEASE, "agent");
;             asm volatile("s_waitcnt vmcnt(0)" ::: "memory");
;             const unsigned og = xb_add(&bar[XB_TOP], 1u);
;             const unsigned tg = og / nx;
;             if (og + 1u == (tg + 1u) * nx) xb_add(&bar[XB_TOPGEN], 1u);
;             else XB_SPIN(xb_ld(&bar[XB_TOPGEN]) == tg, bar);
.LBB0_465:
	s_or_b64 exec, exec, s[18:19]
	v_cvt_f32_u32_e32 v4, v2
	s_waitcnt vmcnt(0)
	v_readfirstlane_b32 s8, v3
	v_sub_u32_e32 v3, 0, v2
	v_rcp_iflag_f32_e32 v4, v4
	v_add_u32_e32 v5, s8, v1
	v_mul_f32_e32 v4, 0x4f7ffffe, v4
	v_cvt_u32_f32_e32 v4, v4
	v_mul_lo_u32 v1, v3, v4
	v_mul_hi_u32 v1, v4, v1
	v_add_u32_e32 v1, v4, v1
	v_mul_hi_u32 v1, v5, v1
	v_mul_lo_u32 v3, v1, v2
	v_sub_u32_e32 v3, v5, v3
	v_add_u32_e32 v4, 1, v1
	v_cmp_ge_u32_e32 vcc, v3, v2
	s_nop 1
	v_cndmask_b32_e32 v1, v1, v4, vcc
	v_sub_u32_e32 v4, v3, v2
	v_cndmask_b32_e32 v3, v3, v4, vcc
	v_add_u32_e32 v4, 1, v1
	v_cmp_ge_u32_e32 vcc, v3, v2
	v_add_u32_e32 v3, 1, v5
	s_nop 0
	v_cndmask_b32_e32 v1, v1, v4, vcc
	v_mul_lo_u32 v4, v2, v1
	v_add_u32_e32 v2, v4, v2
	v_cmp_ne_u32_e32 vcc, v3, v2
	s_waitcnt lgkmcnt(0)
	v_mad_u32_u24 v4, v1, v0, v0
	s_cbranch_vccnz .Lxb1_poll
	global_atomic_add v202, v203, s[74:75] offset:1024

; __device__ __forceinline__ unsigned pk2(float lo, float hi) { unsigned r; asm("v_cvt_pk_bf16_f32 %0, %1, %2" : "=v"(r) : "v"(lo), "v"(hi)); return r; }
; template <class FrameT>
; __device__ __forceinline__ void res_fixup(FrameT& F, const EpiRes& E, const pg8::DpSplit& S) {
;     ...
;     for (int item = blockIdx.x; item < nleft * 8; item += F.G) {
;         const int j = item >> 3, ai = (item >> 2) & 1, m = item & 3;
;         pg8::Unit u; S.unit_of(S.G + j, u);
;         const int r = u.pm * 256 + wr * 64 + fr + ai * 128 + m * 16, col0 = u.pn * 256 + wc * 32 + 8 * fq;
;         float q = 0.f;
; #pragma unroll
;         for (int bj = 0; bj < 2; ++bj) {
;             f32x4 a0 = {0.f, 0.f, 0.f, 0.f}, a1 = {0.f, 0.f, 0.f, 0.f};
; #pragma unroll
;             for (int p = 0; p < 4; ++p) {
;                 const float* sp = S.slab + (size_t)(4 * j + p) * 65536 + (size_t)(((ai * 2 + bj) * 4 + m) * 2048) + tid * 4;
;                 const u32x4 w = __builtin_nontemporal_load((const u32x4*)sp);
;                 a0 += (f32x4){__uint_as_float(w.x << 16), __uint_as_float(w.x & 0xffff0000u), __uint_as_float(w.y << 16), __uint_as_float(w.y & 0xffff0000u)};
;                 a1 += (f32x4){__uint_as_float(w.z << 16), __uint_as_float(w.z & 0xffff0000u), __uint_as_float(w.w << 16), __uint_as_float(w.w & 0xffff0000u)};
;             }
;             float* xp = E.X + (size_t)r * D + col0 + bj * 128;
;             f32x4 v0 = *(f32x4*)xp, v1 = *(f32x4*)(xp + 4);
;             v0 = v0 + a0 * E.scale; v1 = v1 + a1 * E.scale;
;             *(f32x4*)xp = v0; *(f32x4*)(xp + 4) = v1;
;             u32x4 w; w.x = pk2(v0[0], v0[1]); w.y = pk2(v0[2], v0[3]); w.z = pk2(v1[0], v1[1]); w.w = pk2(v1[2], v1[3]);
;             *(u32x4*)(E.XB + (size_t)r * D + col0 + bj * 128) = w;
;             q += (v0[0] * v0[0] + v0[1] * v0[1]) + (v0[2] * v0[2] + v0[3] * v0[3]) + (v1[0] * v1[0] + v1[1] * v1[1]) + (v1[2] * v1[2] + v1[3] * v1[3]);
;         }
.LBB0_506:
	s_add_i32 s2, s9, s2
	s_ashr_i32 s3, s2, 31
	s_lshr_b32 s3, s3, 27
	s_add_i32 s3, s2, s3
	s_ashr_i32 s9, s3, 5
	s_lshl_b32 s9, s9, 3
	s_sub_i32 s20, 0x45, s9
	s_min_i32 s20, s20, 8
	s_abs_i32 s22, s20
	v_cvt_f32_u32_e32 v0, s22
	s_sub_i32 s23, 0, s22
	s_andn2_b32 s3, s3, 31
	s_sub_i32 s2, s2, s3
	v_rcp_iflag_f32_e32 v0, v0
	s_abs_i32 s21, s2
	s_xor_b32 s3, s2, s20
	s_bfe_u32 s18, s17, 0x10002
	v_mul_f32_e32 v0, 0x4f7ffffe, v0
	v_cvt_u32_f32_e32 v0, v0
	s_and_b32 s19, s17, 3
	s_ashr_i32 s3, s3, 31
	v_mov_b32_e32 v175, v174
	v_readfirstlane_b32 s24, v0
	s_mul_i32 s23, s23, s24
	s_mul_hi_u32 s23, s24, s23
	s_add_i32 s24, s24, s23
	s_mul_hi_u32 s23, s21, s24
	s_mul_i32 s24, s23, s22
	s_sub_i32 s21, s21, s24
	s_add_i32 s24, s23, 1
	s_sub_i32 s25, s21, s22
	s_cmp_ge_u32 s21, s22
	s_cselect_b32 s23, s24, s23
	s_cselect_b32 s21, s25, s21
	s_add_i32 s24, s23, 1
	s_cmp_ge_u32 s21, s22
	s_cselect_b32 s21, s24, s23
	s_xor_b32 s21, s21, s3
	s_sub_i32 s3, s21, s3
	s_mul_i32 s20, s3, s20
	s_sub_i32 s2, s2, s20
	s_add_i32 s9, s9, s2
	s_lshl_b32 s2, s9, 8
	s_lshl_b32 s9, s18, 7
	s_lshl_b32 s20, s8, 2
	v_lshl_or_b32 v0, s19, 4, v22
	s_or_b32 s2, s2, s9
	s_ashr_i32 s21, s20, 31
	s_lshl_b32 s8, s19, 13
	s_lshl_b32 s9, s18, 16
	v_add_u32_e32 v8, s2, v0
	v_lshl_or_b32 v2, s3, 8, v23
	s_lshl_b64 s[2:3], s[20:21], 18
	s_or_b32 s8, s9, s8
	s_add_u32 s8, s72, s8
	s_addc_u32 s9, s73, 0
	s_waitcnt lgkmcnt(0)
	v_lshl_add_u64 v[0:1], v[4:5], 2, s[8:9]
	v_lshl_add_u64 v[10:11], v[0:1], 0, s[2:3]
	global_load_dwordx4 v[10:13], v[10:11], off sc1
	s_or_b32 s8, s20, 1
	s_ashr_i32 s9, s8, 31
	s_lshl_b64 s[8:9], s[8:9], 18
	s_or_b32 s18, s20, 2
	s_ashr_i32 s19, s18, 31
	s_lshl_b64 s[18:19], s[18:19], 18
	s_or_b32 s20, s20, 3
	s_ashr_i32 s21, s20, 31
	s_lshl_b64 s[20:21], s[20:21], 18
	v_ashrrev_i32_e32 v9, 31, v8
	v_ashrrev_i32_e32 v3, 31, v2
	s_mov_b64 s[22:23], 0x8000
	v_lshl_add_u64 v[32:33], v[0:1], 0, s[8:9]
	global_load_dwordx4 v[36:39], v[32:33], off
	v_lshl_add_u64 v[34:35], v[32:33], 0, s[22:23]
	global_load_dwordx4 v[36:39], v[34:35], off
	v_lshl_add_u64 v[32:33], v[0:1], 0, s[18:19]
	global_load_dwordx4 v[36:39], v[32:33], off
	v_lshl_add_u64 v[34:35], v[32:33], 0, s[22:23]
	global_load_dwordx4 v[36:39], v[34:35], off
	v_lshl_add_u64 v[32:33], v[0:1], 0, s[20:21]
	global_load_dwordx4 v[36:39], v[32:33], off
	v_lshl_add_u64 v[34:35], v[32:33], 0, s[22:23]
	global_load_dwordx4 v[36:39], v[34:35], off
	v_lshl_add_u64 v[32:33], v[0:1], 0, s[2:3]
	v_lshl_add_u64 v[34:35], v[32:33], 0, s[22:23]
	global_load_dwordx4 v[36:39], v[34:35], off
	v_lshlrev_b64 v[32:33], 12, v[8:9]
	v_lshl_add_u64 v[32:33], s[10:11], 0, v[32:33]
	v_lshl_add_u64 v[32:33], v[2:3], 2, v[32:33]
	global_load_dwordx4 v[36:39], v[32:33], off
	global_load_dwordx4 v[36:39], v[32:33], off offset:512
	s_waitcnt vmcnt(0)
	v_lshlrev_b32_e32 v14, 16, v10
	v_and_b32_e32 v15, 0xffff0000, v10
	v_lshlrev_b32_e32 v10, 16, v11
	v_and_b32_e32 v11, 0xffff0000, v11
	v_pk_add_f32 v[16:17], v[10:11], 0 op_sel_hi:[1,0]
	v_lshlrev_b32_e32 v10, 16, v12
	v_and_b32_e32 v11, 0xffff0000, v12
	v_lshlrev_b32_e32 v12, 16, v13
	v_and_b32_e32 v13, 0xffff0000, v13
	v_pk_add_f32 v[20:21], v[10:11], 0 op_sel_hi:[1,0]
	v_lshl_add_u64 v[10:11], v[0:1], 0, s[8:9]
	v_pk_add_f32 v[18:19], v[12:13], 0 op_sel_hi:[1,0]
	global_load_dwordx4 v[10:13], v[10:11], off sc1
	v_pk_add_f32 v[14:15], v[14:15], 0 op_sel_hi:[1,0]
	s_waitcnt vmcnt(0)
	v_lshlrev_b32_e32 v24, 16, v10
	v_and_b32_e32 v25, 0xffff0000, v10
	v_lshlrev_b32_e32 v10, 16, v11
	v_and_b32_e32 v11, 0xffff0000, v11
	v_pk_add_f32 v[16:17], v[16:17], v[10:11]
	v_lshlrev_b32_e32 v10, 16, v12
	v_and_b32_e32 v11, 0xffff0000, v12
	v_lshlrev_b32_e32 v12, 16, v13
	v_and_b32_e32 v13, 0xffff0000, v13
	v_pk_add_f32 v[20:21], v[20:21], v[10:11]
	v_lshl_add_u64 v[10:11], v[0:1], 0, s[18:19]
	v_pk_add_f32 v[18:19], v[18:19], v[12:13]
	global_load_dwordx4 v[10:13], v[10:11], off sc1
	v_pk_add_f32 v[14:15], v[14:15], v[24:25]
	s_waitcnt vmcnt(0)
	v_lshlrev_b32_e32 v24, 16, v10
	v_and_b32_e32 v25, 0xffff0000, v10
	v_pk_add_f32 v[24:25], v[14:15], v[24:25]
	v_lshlrev_b32_e32 v14, 16, v12
	v_and_b32_e32 v15, 0xffff0000, v12
	v_lshlrev_b32_e32 v12, 16, v13
	v_and_b32_e32 v13, 0xffff0000, v13
	v_lshlrev_b32_e32 v10, 16, v11
	v_and_b32_e32 v11, 0xffff0000, v11
	v_pk_add_f32 v[18:19], v[18:19], v[12:13]
	v_lshl_add_u64 v[12:13], v[0:1], 0, s[20:21]
	v_pk_add_f32 v[10:11], v[16:17], v[10:11]
	v_pk_add_f32 v[20:21], v[20:21], v[14:15]
	global_load_dwordx4 v[14:17], v[12:13], off sc1
	s_waitcnt vmcnt(0)
	v_lshlrev_b32_e32 v12, 16, v14
	v_and_b32_e32 v13, 0xffff0000, v14
	v_lshlrev_b32_e32 v14, 16, v15
	v_and_b32_e32 v15, 0xffff0000, v15
	v_pk_add_f32 v[14:15], v[10:11], v[14:15]
	v_lshlrev_b32_e32 v10, 16, v16
	v_and_b32_e32 v11, 0xffff0000, v16
	v_pk_add_f32 v[12:13], v[24:25], v[12:13]
	v_lshlrev_b32_e32 v24, 16, v17
	v_and_b32_e32 v25, 0xffff0000, v17
	v_pk_add_f32 v[16:17], v[20:21], v[10:11]
	v_lshlrev_b64 v[10:11], 12, v[8:9]
	v_lshl_add_u64 v[10:11], s[10:11], 0, v[10:11]
	v_lshl_add_u64 v[10:11], v[2:3], 2, v[10:11]
	v_pk_add_f32 v[18:19], v[18:19], v[24:25]
	global_load_dwordx4 v[24:27], v[10:11], off offset:16
	global_load_dwordx4 v[28:31], v[10:11], off
	s_waitcnt vmcnt(1)
; __device__ __forceinline__ unsigned pk2(float lo, float hi) { unsigned r; asm("v_cvt_pk_bf16_f32 %0, %1, %2" : "=v"(r) : "v"(lo), "v"(hi)); return r; }
; template <class FrameT>
; __device__ __forceinline__ void res_fixup(FrameT& F, const EpiRes& E, const pg8::DpSplit& S) {
;     ...
;         for (int bj = 0; bj < 2; ++bj) {
;             f32x4 a0 = {0.f, 0.f, 0.f, 0.f}, a1 = {0.f, 0.f, 0.f, 0.f};
; #pragma unroll
;             for (int p = 0; p < 4; ++p) {
;                 const float* sp = S.slab + (size_t)(4 * j + p) * 65536 + (size_t)(((ai * 2 + bj) * 4 + m) * 2048) + tid * 4;
;                 const u32x4 w = __builtin_nontemporal_load((const u32x4*)sp);
;                 a0 += (f32x4){__uint_as_float(w.x << 16), __uint_as_float(w.x & 0xffff0000u), __uint_as_float(w.y << 16), __uint_as_float(w.y & 0xffff0000u)};
;                 a1 += (f32x4){__uint_as_float(w.z << 16), __uint_as_float(w.z & 0xffff0000u), __uint_as_float(w.w << 16), __uint_as_float(w.w & 0xffff0000u)};
;             }
;             float* xp = E.X + (size_t)r * D + col0 + bj * 128;
;             f32x4 v0 = *(f32x4*)xp, v1 = *(f32x4*)(xp + 4);
;             v0 = v0 + a0 * E.scale; v1 = v1 + a1 * E.scale;
;             *(f32x4*)xp = v0; *(f32x4*)(xp + 4) = v1;
;             u32x4 w; w.x = pk2(v0[0], v0[1]); w.y = pk2(v0[2], v0[3]); w.z = pk2(v1[0], v1[1]); w.w = pk2(v1[2], v1[3]);
;             *(u32x4*)(E.XB + (size_t)r * D + col0 + bj * 128) = w;
;             q += (v0[0] * v0[0] + v0[1] * v0[1]) + (v0[2] * v0[2] + v0[3] * v0[3]) + (v1[0] * v1[0] + v1[1] * v1[1]) + (v1[2] * v1[2] + v1[3] * v1[3]);
;         }
;         q += __shfl_xor(q, 16); q += __shfl_xor(q, 32);
;         if (fq == 0) atomicAdd(E.ssn + r, q);
	v_pk_fma_f32 v[16:17], v[6:7], v[16:17], v[24:25]
	s_waitcnt vmcnt(0)
	v_pk_fma_f32 v[28:29], v[6:7], v[12:13], v[28:29]
	v_lshlrev_b64 v[12:13], 11, v[8:9]
	v_pk_fma_f32 v[30:31], v[174:175], v[14:15], v[30:31]
	v_lshl_add_u64 v[12:13], s[12:13], 0, v[12:13]
	v_lshl_add_u64 v[12:13], v[2:3], 1, v[12:13]
	v_mul_f32_e32 v2, v29, v29
	v_mul_f32_e32 v3, v31, v31
	v_fmac_f32_e32 v2, v28, v28
	v_fmac_f32_e32 v3, v30, v30
	v_add_f32_e32 v2, v2, v3
	v_mul_f32_e32 v3, v17, v17
	v_pk_fma_f32 v[18:19], v[174:175], v[18:19], v[26:27]
	v_fmac_f32_e32 v3, v16, v16
	v_add_f32_e32 v2, v3, v2
	v_mul_f32_e32 v3, v19, v19
	v_lshl_add_u64 v[14:15], v[0:1], 0, s[22:23]
	global_store_dwordx4 v[10:11], v[28:31], off
	global_store_dwordx4 v[10:11], v[16:19], off offset:16
	v_cvt_pk_bf16_f32 v24, v28, v29
	v_cvt_pk_bf16_f32 v25, v30, v31
	v_cvt_pk_bf16_f32 v26, v16, v17
	v_cvt_pk_bf16_f32 v27, v18, v19
	global_store_dwordx4 v[12:13], v[24:27], off
	v_fmac_f32_e32 v3, v18, v18
	v_lshl_add_u64 v[0:1], v[14:15], 0, s[2:3]
	v_add_f32_e32 v24, v3, v2
	global_load_dwordx4 v[0:3], v[0:1], off sc1
	s_waitcnt vmcnt(0)
	v_lshlrev_b32_e32 v16, 16, v0
	v_and_b32_e32 v17, 0xffff0000, v0
	v_lshlrev_b32_e32 v0, 16, v1
	v_and_b32_e32 v1, 0xffff0000, v1
	v_pk_add_f32 v[18:19], v[0:1], 0 op_sel_hi:[1,0]
	v_lshlrev_b32_e32 v0, 16, v2
	v_and_b32_e32 v1, 0xffff0000, v2
	v_lshlrev_b32_e32 v2, 16, v3
	v_and_b32_e32 v3, 0xffff0000, v3
	v_pk_add_f32 v[26:27], v[0:1], 0 op_sel_hi:[1,0]
	v_lshl_add_u64 v[0:1], v[14:15], 0, s[8:9]
	v_pk_add_f32 v[20:21], v[2:3], 0 op_sel_hi:[1,0]
	global_load_dwordx4 v[0:3], v[0:1], off sc1
	v_pk_add_f32 v[16:17], v[16:17], 0 op_sel_hi:[1,0]
	s_waitcnt vmcnt(0)
	v_lshlrev_b32_e32 v28, 16, v0
	v_and_b32_e32 v29, 0xffff0000, v0
	v_lshlrev_b32_e32 v0, 16, v1
	v_and_b32_e32 v1, 0xffff0000, v1
	v_pk_add_f32 v[18:19], v[18:19], v[0:1]
	v_lshlrev_b32_e32 v0, 16, v2
	v_and_b32_e32 v1, 0xffff0000, v2
	v_lshlrev_b32_e32 v2, 16, v3
	v_and_b32_e32 v3, 0xffff0000, v3
	v_pk_add_f32 v[26:27], v[26:27], v[0:1]
	v_lshl_add_u64 v[0:1], v[14:15], 0, s[18:19]
	v_pk_add_f32 v[20:21], v[20:21], v[2:3]
	global_load_dwordx4 v[0:3], v[0:1], off sc1
	v_pk_add_f32 v[16:17], v[16:17], v[28:29]
	s_waitcnt vmcnt(0)
	v_lshlrev_b32_e32 v28, 16, v0
	v_and_b32_e32 v29, 0xffff0000, v0
	v_lshlrev_b32_e32 v0, 16, v1
	v_and_b32_e32 v1, 0xffff0000, v1
	v_pk_add_f32 v[18:19], v[18:19], v[0:1]
	v_lshlrev_b32_e32 v0, 16, v2
	v_and_b32_e32 v1, 0xffff0000, v2
	v_lshlrev_b32_e32 v2, 16, v3
	v_and_b32_e32 v3, 0xffff0000, v3
	v_pk_add_f32 v[26:27], v[26:27], v[0:1]
	v_lshl_add_u64 v[0:1], v[14:15], 0, s[20:21]
	v_pk_add_f32 v[20:21], v[20:21], v[2:3]
	global_load_dwordx4 v[0:3], v[0:1], off sc1
	v_pk_add_f32 v[16:17], v[16:17], v[28:29]
	s_waitcnt vmcnt(0)
	v_lshlrev_b32_e32 v14, 16, v0
	v_and_b32_e32 v15, 0xffff0000, v0
	v_lshlrev_b32_e32 v0, 16, v1
	v_and_b32_e32 v1, 0xffff0000, v1
	v_pk_add_f32 v[14:15], v[16:17], v[14:15]
	v_pk_add_f32 v[16:17], v[18:19], v[0:1]
	v_lshlrev_b32_e32 v0, 16, v2
	v_and_b32_e32 v1, 0xffff0000, v2
	v_lshlrev_b32_e32 v2, 16, v3
	v_and_b32_e32 v3, 0xffff0000, v3
	v_pk_add_f32 v[18:19], v[26:27], v[0:1]
	v_pk_add_f32 v[20:21], v[20:21], v[2:3]
	global_load_dwordx4 v[0:3], v[10:11], off offset:528
	global_load_dwordx4 v[26:29], v[10:11], off offset:512
	s_waitcnt vmcnt(1)
	v_pk_fma_f32 v[2:3], v[174:175], v[20:21], v[2:3]
	s_waitcnt vmcnt(0)
	v_pk_fma_f32 v[16:17], v[174:175], v[16:17], v[28:29]
	v_pk_fma_f32 v[14:15], v[6:7], v[14:15], v[26:27]
	v_pk_fma_f32 v[0:1], v[6:7], v[18:19], v[0:1]
	global_store_dwordx4 v[10:11], v[14:17], off offset:512
	global_store_dwordx4 v[10:11], v[0:3], off offset:528
	v_mul_f32_e32 v10, v15, v15
	v_mul_f32_e32 v11, v17, v17
	v_cvt_pk_bf16_f32 v20, v0, v1
	v_fmac_f32_e32 v10, v14, v14
	v_fmac_f32_e32 v11, v16, v16
	v_mul_f32_e32 v1, v1, v1
	v_add_f32_e32 v10, v10, v11
	v_fmac_f32_e32 v1, v0, v0
	v_add_f32_e32 v0, v1, v10
	v_mul_f32_e32 v1, v3, v3
	v_fmac_f32_e32 v1, v2, v2
	v_cvt_pk_bf16_f32 v21, v2, v3
	v_add_f32_e32 v0, v1, v0
	v_xor_b32_e32 v1, 16, v196
	v_add_u32_e32 v2, 64, v197
	v_cmp_lt_i32_e32 vcc, v1, v2
	v_add_f32_e32 v0, v24, v0
	v_cvt_pk_bf16_f32 v18, v14, v15
	v_cvt_pk_bf16_f32 v19, v16, v17
	global_store_dwordx4 v[12:13], v[18:21], off offset:256
	v_cndmask_b32_e32 v1, v196, v1, vcc
	v_lshlrev_b32_e32 v1, 2, v1
	ds_bpermute_b32 v1, v1, v0
	s_waitcnt lgkmcnt(0)
	v_add_f32_e32 v0, v0, v1
	v_xor_b32_e32 v1, 32, v196
	v_cmp_lt_i32_e32 vcc, v1, v2
	s_nop 1
	v_cndmask_b32_e32 v1, v196, v1, vcc
	v_lshlrev_b32_e32 v1, 2, v1
	ds_bpermute_b32 v1, v1, v0
	s_and_saveexec_b64 s[2:3], s[6:7]
	s_cbranch_execz .LBB0_501
	v_lshl_add_u64 v[2:3], v[8:9], 2, s[14:15]
	s_waitcnt lgkmcnt(0)
	v_add_f32_e32 v0, v0, v1
	global_atomic_add_f32 v[2:3], v0, off
	s_branch .LBB0_501
